# mode D: second-half row-sum add chain deferred into next first-half QK MFMA shadow (s1 MFMAs first, K temps renamed)
# speedup vs baseline: 1.0028x; 1.0028x over previous
; DI unsigned pack2(float a, float b) { f32x2 v = {a, b}; bf16v2 r = __builtin_convertvector(v, bf16v2); return __builtin_bit_cast(unsigned, r); }
; template <int MODE>
; DI void attn_tile(const Params& p, int layer, int tile, char* smem) {
;     ...
;   if (MODE == 3) {
;     bf16x8 x1 = qf[NKQ - 2], x2 = qf[NKQ - 1];
;     const f32x4* rt = (const f32x4*)(p.ws + OFF_ROPE) + (size_t)qpos * 8 + 4 * h;
; #pragma unroll
;     for (int j2 = 0; j2 < 4; ++j2) {
;       const f32x4 cs4 = rt[j2];
; #pragma unroll
;       for (int e = 0; e < 2; ++e) {
;         const int j = 2 * j2 + e;
;         const float c = cs4[2 * e], sn = cs4[2 * e + 1];
;         float a = __uint_as_float(((unsigned)(u16)x1[j]) << 16), b = __uint_as_float(((unsigned)(u16)x2[j]) << 16);
;         unsigned w = pack2(a * c - b * sn, a * sn + b * c);
;         x1[j] = (short)(w & 0xffff); x2[j] = (short)(w >> 16);
;       }
;     }
;     qf[NKQ - 2] = x1; qf[NKQ - 1] = x2;
;   }
;   u32x4 rk0[KLD], rv0, rk1[KLD], rv1;
;   const u16* Kt = Kp + tok0 * ldk;
;   const u16* Vt = Vp + tok0 * ldv;
;   unsigned koff[KLD];
; #pragma unroll
;   for (int pp = 0; pp < KLD; ++pp) { int c = tid + NTHR * pp; if (c >= 64 * KCH) c = tid; const int row = c / KCH, col = c % KCH; koff[pp] = (unsigned)row * ldk + col * 8; }
;   const unsigned voff = (unsigned)(tid >> 3) * ldv + (tid & 7) * 8;
;   const int ktl = kt1 - 1;
;   auto gload = [&](u32x4 (&rk)[KLD], u32x4& rv, int kt) {
;     kt = kt < ktl ? kt : ktl;
; #pragma unroll
;     for (int pp = 0; pp < KLD; ++pp) rk[pp] = *(const u32x4*)(Kt + (koff[pp] + (unsigned)(kt * 64) * ldk));
;     rv = *(const u32x4*)(Vt + (voff + (unsigned)(kt * 64) * ldv));
;   };
;   auto lstore = [&](u32x4 (&rk)[KLD], u32x4& rv, int buf) {
; #pragma unroll
;     for (int pp = 0; pp < KLD; ++pp) { const int c = tid + NTHR * pp; if (c < 64 * KCH) { const int row = c / KCH, col = c % KCH; *(u32x4*)(Ks + (buf * 64 + row) * KROW + col * 8) = rk[pp]; } }
;     *(u32x4*)(Vs + (buf * 64 + (tid >> 3)) * VROW + (tid & 7) * 8) = rv;
;   };
;   f32x16 o0, o1, negm;
; #pragma unroll
;   for (int i = 0; i < 16; ++i) { o0[i] = 0.f; o1[i] = 0.f; negm[i] = 0.f; }
;   float mref = 0.f, lsum = 0.f;
.LBB0_114:
	s_or_b64 exec, exec, s[0:1]
	s_waitcnt vmcnt(4)
	v_lshlrev_b32_e32 v30, 16, v6
	v_lshlrev_b32_e32 v0, 16, v2
	v_pk_mul_f32 v[30:31], v[26:27], v[30:31] op_sel:[1,0] op_sel_hi:[0,0]
	v_pk_fma_f32 v[32:33], v[26:27], v[0:1], v[30:31] neg_lo:[0,0,1] neg_hi:[0,0,1]
	v_pk_fma_f32 v[26:27], v[26:27], v[0:1], v[30:31] op_sel_hi:[1,0,1]
	v_and_b32_e32 v0, 0xffff0000, v2
	v_and_b32_e32 v2, 0xffff0000, v6
	v_cvt_pk_bf16_f32 v32, v32, v27
	v_pk_mul_f32 v[26:27], v[28:29], v[2:3] op_sel:[1,0] op_sel_hi:[0,0]
	v_pk_fma_f32 v[30:31], v[28:29], v[0:1], v[26:27] neg_lo:[0,0,1] neg_hi:[0,0,1]
	v_pk_fma_f32 v[26:27], v[28:29], v[0:1], v[26:27] op_sel_hi:[1,0,1]
	v_lshlrev_b32_e32 v2, 16, v7
	v_cvt_pk_bf16_f32 v6, v30, v27
	v_lshlrev_b32_e32 v0, 16, v3
	v_pk_mul_f32 v[26:27], v[22:23], v[2:3] op_sel:[1,0] op_sel_hi:[0,0]
	v_and_b32_e32 v2, 0xffff0000, v7
	s_mov_b32 s0, 0x5040100
	v_pk_fma_f32 v[28:29], v[22:23], v[0:1], v[26:27] neg_lo:[0,0,1] neg_hi:[0,0,1]
	v_pk_fma_f32 v[22:23], v[22:23], v[0:1], v[26:27] op_sel_hi:[1,0,1]
	s_mov_b32 s1, 0x7060302
	v_and_b32_e32 v0, 0xffff0000, v3
	v_pk_mul_f32 v[2:3], v[24:25], v[2:3] op_sel:[1,0] op_sel_hi:[0,0]
	v_perm_b32 v126, v6, v32, s0
	v_perm_b32 v130, v6, v32, s1
	v_pk_fma_f32 v[6:7], v[24:25], v[0:1], v[2:3] neg_lo:[0,0,1] neg_hi:[0,0,1]
	v_pk_fma_f32 v[2:3], v[24:25], v[0:1], v[2:3] op_sel_hi:[1,0,1]
	v_cvt_pk_bf16_f32 v22, v28, v23
	v_cvt_pk_bf16_f32 v0, v6, v3
	v_perm_b32 v127, v0, v22, s0
	v_perm_b32 v131, v0, v22, s1
	v_lshlrev_b32_e32 v0, 16, v8
	v_pk_mul_f32 v[6:7], v[14:15], v[0:1] op_sel:[1,0] op_sel_hi:[0,0]
	v_add_u32_e32 v0, 0xc000, v182
	v_lshl_add_u64 v[24:25], v[0:1], 1, s[14:15]
	v_add_u32_e32 v0, 0xc000, v184
	v_lshl_add_u64 v[26:27], v[0:1], 1, s[14:15]
	v_add_u32_e32 v0, 0x8000, v186
	global_load_dwordx4 v[138:141], v[24:25], off
	global_load_dwordx4 v[142:145], v[26:27], off
	v_lshl_add_u64 v[24:25], v[0:1], 1, s[16:17]
	global_load_dwordx4 v[134:137], v[24:25], off
	v_lshlrev_b32_e32 v2, 16, v4
	v_pk_fma_f32 v[22:23], v[14:15], v[2:3], v[6:7] neg_lo:[0,0,1] neg_hi:[0,0,1]
	v_pk_fma_f32 v[2:3], v[14:15], v[2:3], v[6:7] op_sel_hi:[1,0,1]
	v_and_b32_e32 v0, 0xffff0000, v4
	v_and_b32_e32 v2, 0xffff0000, v8
	v_cvt_pk_bf16_f32 v14, v22, v3
	v_pk_mul_f32 v[2:3], v[16:17], v[2:3] op_sel:[1,0] op_sel_hi:[0,0]
	v_pk_fma_f32 v[6:7], v[16:17], v[0:1], v[2:3] neg_lo:[0,0,1] neg_hi:[0,0,1]
	v_pk_fma_f32 v[2:3], v[16:17], v[0:1], v[2:3] op_sel_hi:[1,0,1]
	v_lshlrev_b32_e32 v185, 2, v39
	v_cvt_pk_bf16_f32 v0, v6, v3
	v_lshlrev_b32_e32 v2, 16, v9
	v_perm_b32 v128, v0, v14, s0
	v_perm_b32 v132, v0, v14, s1
	v_lshlrev_b32_e32 v0, 16, v5
	v_pk_mul_f32 v[2:3], v[10:11], v[2:3] op_sel:[1,0] op_sel_hi:[0,0]
	v_pk_fma_f32 v[6:7], v[10:11], v[0:1], v[2:3] neg_lo:[0,0,1] neg_hi:[0,0,1]
	v_pk_fma_f32 v[2:3], v[10:11], v[0:1], v[2:3] op_sel_hi:[1,0,1]
	v_and_b32_e32 v0, 0xffff0000, v5
	v_and_b32_e32 v2, 0xffff0000, v9
	v_cvt_pk_bf16_f32 v6, v6, v3
	v_pk_mul_f32 v[2:3], v[12:13], v[2:3] op_sel:[1,0] op_sel_hi:[0,0]
	v_pk_fma_f32 v[4:5], v[12:13], v[0:1], v[2:3] neg_lo:[0,0,1] neg_hi:[0,0,1]
	v_pk_fma_f32 v[2:3], v[12:13], v[0:1], v[2:3] op_sel_hi:[1,0,1]
	v_lshlrev_b32_e32 v40, 3, v39
	v_cvt_pk_bf16_f32 v0, v4, v3
	v_perm_b32 v129, v0, v6, s0
	v_perm_b32 v133, v0, v6, s1
	v_lshrrev_b32_e32 v0, 2, v34
	v_and_b32_e32 v2, 16, v34
	v_and_or_b32 v0, v0, 3, v185
	v_and_b32_e32 v4, 24, v35
	v_mul_lo_u32 v3, v36, s87
	v_lshl_or_b32 v2, v2, 1, v4
	v_mul_u32_u24_e32 v0, 0x48, v0
	v_lshl_add_u32 v190, v189, 1, v3
	v_mul_u32_u24_e32 v3, 0x68, v179
	v_lshl_add_u32 v191, v0, 1, v2
	v_lshlrev_b32_e32 v0, 1, v40
	v_lshl_add_u32 v192, v3, 1, v0
	v_lshlrev_b32_e32 v0, 1, v38
	v_mov_b32_e32 v14, v1
	v_mov_b32_e32 v15, v1
	s_waitcnt vmcnt(6)
	ds_write_b128 v190, v[18:21] offset:26624
	v_lshl_add_u32 v193, v37, 1, v0
	v_mov_b32_e32 v0, v1
	v_mov_b32_e32 v2, v1
	v_mov_b32_e32 v3, v1
	v_mov_b32_e32 v4, v1
	v_mov_b32_e32 v5, v1
	v_mov_b32_e32 v6, v1
	v_mov_b32_e32 v7, v1
	v_mov_b32_e32 v8, v1
	v_mov_b32_e32 v9, v1
	v_mov_b32_e32 v10, v1
	v_mov_b32_e32 v11, v1
	v_mov_b32_e32 v12, v1
	v_mov_b32_e32 v13, v1
	v_mov_b64_e32 v[32:33], v[14:15]
	v_mov_b32_e32 v210, 0
	v_mov_b64_e32 v[30:31], v[12:13]
	v_mov_b64_e32 v[28:29], v[10:11]
	v_mov_b64_e32 v[26:27], v[8:9]
	v_mov_b64_e32 v[24:25], v[6:7]
	v_mov_b64_e32 v[22:23], v[4:5]
	v_mov_b64_e32 v[20:21], v[2:3]
	v_mov_b64_e32 v[18:19], v[0:1]
	v_mov_b64_e32 v[16:17], v[14:15]
	v_and_b32_e32 v183, 63, v34
	s_lshl_b32 s20, s19, 6
	v_mov_b32_e32 v211, 0
	v_mov_b32_e32 v234, 0xefa18f08
	s_mov_b32 s21, -2
	v_mov_b32_e32 v212, 0
	v_mov_b64_e32 v[14:15], v[12:13]
	v_mov_b64_e32 v[12:13], v[10:11]
	v_mov_b64_e32 v[10:11], v[8:9]
	v_mov_b64_e32 v[8:9], v[6:7]
	v_mov_b64_e32 v[6:7], v[4:5]
	v_mov_b64_e32 v[4:5], v[2:3]
	v_mov_b64_e32 v[2:3], v[0:1]
	v_mov_b32_e32 v34, 0
	v_mov_b32_e32 v35, v210
	v_mov_b32_e32 v36, v210
	v_mov_b32_e32 v37, v210
	v_mov_b32_e32 v38, v210
	v_mov_b32_e32 v39, v210
	v_mov_b32_e32 v40, v210
	v_mov_b32_e32 v41, v210
	v_mov_b32_e32 v42, v210
	v_mov_b32_e32 v43, v210
	v_mov_b32_e32 v44, v210
	v_mov_b32_e32 v45, v210
	v_mov_b32_e32 v46, v210
	v_mov_b32_e32 v47, v210
	v_mov_b32_e32 v48, v210
	v_mov_b32_e32 v49, v210
	v_mov_b32_e32 v50, 0
	v_mov_b32_e32 v51, 0
	v_mov_b32_e32 v52, 0
	v_mov_b32_e32 v53, 0
	v_mov_b32_e32 v54, 0
	v_mov_b32_e32 v55, 0
	v_mov_b32_e32 v56, 0
	v_mov_b32_e32 v57, 0
	v_mov_b32_e32 v58, 0
	v_mov_b32_e32 v59, 0
	v_mov_b32_e32 v60, 0
	v_mov_b32_e32 v61, 0
	v_mov_b32_e32 v62, 0
	v_mov_b32_e32 v63, 0
	v_mov_b32_e32 v64, 0
	v_mov_b32_e32 v65, 0
	v_mov_b32_e32 v66, 0
	v_mov_b32_e32 v67, 0
	v_mov_b32_e32 v68, 0
	v_mov_b32_e32 v69, 0
	v_mov_b32_e32 v70, 0
	v_mov_b32_e32 v71, 0
	v_mov_b32_e32 v72, 0
	v_mov_b32_e32 v73, 0
	v_mov_b32_e32 v74, 0
	v_mov_b32_e32 v75, 0
	v_mov_b32_e32 v76, 0
	v_mov_b32_e32 v77, 0
	v_mov_b32_e32 v78, 0
	v_mov_b32_e32 v79, 0
	v_mov_b32_e32 v80, 0
	v_mov_b32_e32 v81, 0
	v_mov_b32_e32 v162, 0
	s_waitcnt lgkmcnt(0)
	s_barrier
	s_branch .LBB0_116
; DI f32x16 mfma(bf16x8 a, bf16x8 b, f32x16 c) { return __builtin_amdgcn_mfma_f32_32x32x16_bf16(a, b, c, 0, 0, 0); }
; template <int MODE>
; DI void attn_tile(const Params& p, int layer, int tile, char* smem) {
;     ...
;       f32x16 s0 = negm, s1 = negm;
; #pragma unroll
;       for (int d0 = 0; d0 < NKQ; ++d0) {
;         bf16x8 k0 = *(const bf16x8*)(Kb + d0 * 16);
;         bf16x8 k1 = *(const bf16x8*)(Kb + 32 * KROW + d0 * 16);
;         s0 = mfma(k0, qf[d0], s0);
;         s1 = mfma(k1, qf[d0], s1);
;       }
;       if (MODE == 0) {
;         const float* tb = tbl + (kt * 64 + 4 * h - qpos + 1280);
; #pragma unroll
;         for (int i = 0; i < 16; ++i) { s0[i] += tb[(i & 3) + 8 * (i >> 2)]; s1[i] += tb[32 + (i & 3) + 8 * (i >> 2)]; }
;       }
;       if (MODE == 2) {
;         const float* tb = tbl + (kt - qr + 7) * 31 + (15 - qc);
; #pragma unroll
;         for (int i = 0; i < 16; ++i) {
;           const int kc0 = 4 * h + (i & 3) + 8 * (i >> 2), kc1 = kc0 + 32;
;           const bool v0 = (kc0 >= cs) && (kc0 < cs + 16), v1 = (kc1 >= cs) && (kc1 < cs + 16);
;           const float b0 = tb[v0 ? kc0 : qc], b1 = tb[v1 ? kc1 : qc];
;           s0[i] = v0 ? s0[i] + b0 : NEGBIG;
;           s1[i] = v1 ? s1[i] + b1 : NEGBIG;
;         }
;       }
;       float ma = __builtin_fmaxf(__builtin_fmaxf(s0[0], s0[1]), s0[2]), mb = __builtin_fmaxf(__builtin_fmaxf(s1[0], s1[1]), s1[2]);
; #pragma unroll
;       for (int i = 3; i < 15; i += 2) { ma = __builtin_fmaxf(__builtin_fmaxf(ma, s0[i]), s0[i + 1]); mb = __builtin_fmaxf(__builtin_fmaxf(mb, s1[i]), s1[i + 1]); }
;       float mt = __builtin_fmaxf(__builtin_fmaxf(ma, s0[15]), s1[15]);
;       mt = hmax(__builtin_fmaxf(mt, mb));
;     ...
;     lstore(rk0, rv0, 1);
;     gload(rk0, rv0, kt0 + j + 3);
;     __syncthreads();
;     if (j + 1 >= ntile) break;
;     compute(1, kt0 + j + 1);
;     lstore(rk1, rv1, 0);
;     gload(rk1, rv1, kt0 + j + 4);
;     __syncthreads();
;   }
.LBB0_115:
	s_or_b64 exec, exec, s[0:1]
	s_min_u32 s0, s21, 59
	s_lshl_b32 s0, s0, 6
	s_addk_i32 s0, 0x100
	s_mul_i32 s1, s0, 0x180
	v_mov_b32_e32 v212, v0
	v_add_u32_e32 v0, s1, v182
	v_lshl_add_u64 v[208:209], v[0:1], 1, s[14:15]
	v_add_u32_e32 v0, s1, v184
	global_load_dwordx4 v[138:141], v[208:209], off
	v_lshl_add_u64 v[208:209], v[0:1], 1, s[14:15]
	v_lshl_add_u32 v0, s0, 8, v186
	global_load_dwordx4 v[142:145], v[208:209], off
	v_lshl_add_u64 v[208:209], v[0:1], 1, s[16:17]
	s_waitcnt vmcnt(5)
	ds_write_b128 v190, v[134:137] offset:26624
	global_load_dwordx4 v[134:137], v[208:209], off
	s_cmp_lt_u32 s21, 62
	s_waitcnt lgkmcnt(0)
	s_barrier
	s_cbranch_scc0 .LBB0_129
.LBB0_116:
	ds_read_b128 v[248:251], v192 offset:6656
	ds_read_b128 v[238:241], v192 offset:6688
	ds_read_b128 v[242:245], v192 offset:6720
	v_add_f32_e32 v50, v50, v66
	v_add_f32_e32 v50, 0, v50
	v_add_f32_e32 v51, v51, v67
	s_waitcnt lgkmcnt(2)
	v_mfma_f32_32x32x16_bf16 v[82:97], v[248:251], v[98:101], v[34:49]
	ds_read_b128 v[248:251], v192 offset:6752
	v_add_f32_e32 v50, v51, v50
	v_add_f32_e32 v51, v52, v68
	v_add_f32_e32 v50, v51, v50
	v_add_f32_e32 v51, v53, v69
	v_add_f32_e32 v50, v51, v50
	v_add_f32_e32 v51, v54, v70
	s_waitcnt lgkmcnt(2)
	v_mfma_f32_32x32x16_bf16 v[82:97], v[238:241], v[102:105], v[82:97]
	ds_read_b128 v[238:241], v192 offset:6784
	v_add_f32_e32 v50, v51, v50
	v_add_f32_e32 v51, v55, v71
	v_add_f32_e32 v50, v51, v50
	v_add_f32_e32 v51, v56, v72
	v_add_f32_e32 v50, v51, v50
	v_add_f32_e32 v51, v162, v73
	s_waitcnt lgkmcnt(2)
	v_mfma_f32_32x32x16_bf16 v[82:97], v[242:245], v[106:109], v[82:97]
	ds_read_b128 v[242:245], v192 offset:6816
	v_add_f32_e32 v50, v51, v50
	v_add_f32_e32 v51, v74, v57
	v_add_f32_e32 v50, v51, v50
	v_add_f32_e32 v51, v75, v58
	v_add_f32_e32 v50, v51, v50
	v_add_f32_e32 v51, v76, v59
	s_waitcnt lgkmcnt(2)
	v_mfma_f32_32x32x16_bf16 v[82:97], v[248:251], v[110:113], v[82:97]
	ds_read_b128 v[248:251], v192
	v_add_f32_e32 v50, v51, v50
	v_add_f32_e32 v51, v77, v60
	v_add_f32_e32 v50, v51, v50
	v_add_f32_e32 v51, v78, v61
	v_add_f32_e32 v50, v51, v50
	v_add_f32_e32 v51, v79, v62
	s_waitcnt lgkmcnt(2)
	v_mfma_f32_32x32x16_bf16 v[82:97], v[238:241], v[126:129], v[82:97]
	ds_read_b128 v[238:241], v192 offset:32
	v_add_f32_e32 v50, v51, v50
	v_add_f32_e32 v51, v80, v63
	v_add_f32_e32 v50, v51, v50
	v_add_f32_e32 v51, v65, v64
	v_add_f32_e32 v50, v51, v50
	s_waitcnt lgkmcnt(2)
	v_mfma_f32_32x32x16_bf16 v[82:97], v[242:245], v[130:133], v[82:97]
	ds_read_b128 v[242:245], v192 offset:64
	v_add_f32_e32 v212, v212, v50
	s_waitcnt lgkmcnt(2)
	v_mfma_f32_32x32x16_bf16 v[66:81], v[248:251], v[98:101], v[34:49]
	ds_read_b128 v[248:251], v192 offset:96
	s_waitcnt lgkmcnt(2)
	v_mfma_f32_32x32x16_bf16 v[66:81], v[238:241], v[102:105], v[66:81]
	ds_read_b128 v[238:241], v192 offset:128
	s_waitcnt lgkmcnt(2)
	v_mfma_f32_32x32x16_bf16 v[66:81], v[242:245], v[106:109], v[66:81]
	ds_read_b128 v[242:245], v192 offset:160
	ds_read_b64_tr_b16 v[174:175], v191 offset:26624
	ds_read_b64_tr_b16 v[176:177], v191 offset:27776
	ds_read_b64_tr_b16 v[172:173], v191 offset:27840
	ds_read_b64_tr_b16 v[170:171], v191 offset:26688
	ds_read_b64_tr_b16 v[166:167], v191 offset:28928
	ds_read_b64_tr_b16 v[168:169], v191 offset:30080
	ds_read_b64_tr_b16 v[164:165], v191 offset:30144
	ds_read_b64_tr_b16 v[162:163], v191 offset:28992
	ds_read_b64_tr_b16 v[158:159], v191 offset:31232
	ds_read_b64_tr_b16 v[160:161], v191 offset:32384
	ds_read_b64_tr_b16 v[156:157], v191 offset:32448
	ds_read_b64_tr_b16 v[154:155], v191 offset:31296
	ds_read_b64_tr_b16 v[146:147], v191 offset:33536
	ds_read_b64_tr_b16 v[148:149], v191 offset:34688
	ds_read_b64_tr_b16 v[152:153], v191 offset:34752
	ds_read_b64_tr_b16 v[150:151], v191 offset:33600
	s_waitcnt lgkmcnt(15)
	v_mfma_f32_32x32x16_bf16 v[66:81], v[248:251], v[110:113], v[66:81]
	v_mfma_f32_32x32x16_bf16 v[66:81], v[238:241], v[126:129], v[66:81]
	v_mfma_f32_32x32x16_bf16 v[66:81], v[242:245], v[130:133], v[66:81]
	s_nop 9
	v_max3_f32 v50, v82, v83, v84
	v_max3_f32 v50, v50, v85, v86
	v_max3_f32 v50, v50, v87, v88
	v_max3_f32 v50, v50, v89, v90
	v_max3_f32 v50, v50, v91, v92
	v_max3_f32 v50, v50, v93, v94
	v_max3_f32 v50, v50, v95, v96
	v_max_f32_e32 v0, v67, v67
	v_max_f32_e32 v208, v66, v66
	v_max_f32_e32 v0, v208, v0
	v_max3_f32 v0, v0, v68, v69
	v_max3_f32 v0, v0, v70, v71
	v_max3_f32 v0, v0, v72, v73
	v_max3_f32 v0, v0, v74, v75
	v_max3_f32 v0, v0, v76, v77
	v_max3_f32 v0, v0, v78, v79
	v_max3_f32 v0, v0, v80, v81
	v_max3_f32 v0, v0, v97, v50
	v_mov_b32_e32 v50, v0
	s_nop 1
	v_permlane32_swap_b32_e32 v0, v50
	v_max_f32_e32 v50, v50, v50
	v_max_f32_e32 v0, v0, v0
	v_max_f32_e32 v0, v0, v50
	v_cmp_lt_f32_e32 vcc, v234, v0
	s_cbranch_vccz .LBB0_118
; DI unsigned pack2(float a, float b) { f32x2 v = {a, b}; bf16v2 r = __builtin_convertvector(v, bf16v2); return __builtin_bit_cast(unsigned, r); }
; DI f32x16 mfma(bf16x8 a, bf16x8 b, f32x16 c) { return __builtin_amdgcn_mfma_f32_32x32x16_bf16(a, b, c, 0, 0, 0); }
; DI float fexp2(float x) { return __builtin_amdgcn_exp2f(x); }
; template <int MODE>
; DI void attn_tile(const Params& p, int layer, int tile, char* smem) {
;     ...
;       if (__any(fresh || (started && mt > 8.f))) {
;         float delta = 0.f, al = 1.f;
;         if (fresh) { delta = mt; started = true; }
;         else if (started) { delta = __builtin_fmaxf(mt, 0.f); al = fexp2(-delta); }
;         mref += delta;
;         lsum *= al;
; #pragma unroll
;         for (int i = 0; i < 16; ++i) { o0[i] *= al; o1[i] *= al; s0[i] -= delta; s1[i] -= delta; negm[i] = -mref; }
;       }
;       float ps = 0.f;
; #pragma unroll
;       for (int i = 0; i < 16; ++i) { s0[i] = fexp2(s0[i]); s1[i] = fexp2(s1[i]); ps += s0[i] + s1[i]; }
;       lsum += ps;
; #pragma unroll
;       for (int c = 0; c < 2; ++c) {
; #pragma unroll
;         for (int s = 0; s < 2; ++s) {
;           u32x4 pw;
;           if (c == 0) pw = (u32x4){pack2(s0[8 * s], s0[8 * s + 1]), pack2(s0[8 * s + 2], s0[8 * s + 3]), pack2(s0[8 * s + 4], s0[8 * s + 5]), pack2(s0[8 * s + 6], s0[8 * s + 7])};
;           else pw = (u32x4){pack2(s1[8 * s], s1[8 * s + 1]), pack2(s1[8 * s + 2], s1[8 * s + 3]), pack2(s1[8 * s + 4], s1[8 * s + 5]), pack2(s1[8 * s + 6], s1[8 * s + 7])};
;           const bf16x8 pf = __builtin_bit_cast(bf16x8, pw);
;           o0 = mfma(vf[2 * (2 * c + s)], pf, o0);
;           o1 = mfma(vf[2 * (2 * c + s) + 1], pf, o1);
;         }
;       }
	v_and_b32_e32 v50, 1, v211
	v_cmp_eq_u32_e64 s[12:13], 1, v50
	v_cmp_nlt_f32_e64 s[10:11], s33, v0
	s_nop 0
	v_max_f32_e32 v34, v0, v0
	v_max_f32_e32 v34, 0, v34
	v_exp_f32_e64 v35, -v34
	v_cndmask_b32_e64 v0, v0, 0, s[10:11]
	v_cndmask_b32_e64 v0, v0, v34, s[12:13]
	v_add_f32_e32 v210, v210, v0
	s_or_b64 vcc, s[10:11], s[12:13]
	v_cndmask_b32_e64 v34, 1.0, v35, s[12:13]
	v_xor_b32_e32 v50, 0x80000000, v210
	v_cndmask_b32_e32 v211, 1, v211, vcc
	v_and_b32_e32 v235, 1, v211
	v_cmp_eq_u32_e32 vcc, 1, v235
	v_mov_b32_e32 v235, 0x41000000
	v_mov_b32_e32 v236, 0xefa18f08
	v_cndmask_b32_e32 v234, v236, v235, vcc
	v_mul_f32_e32 v212, v212, v34
	v_pk_add_f32 v[66:67], v[66:67], v[0:1] op_sel_hi:[1,0] neg_lo:[0,1] neg_hi:[0,1]
	v_pk_add_f32 v[82:83], v[82:83], v[0:1] op_sel_hi:[1,0] neg_lo:[0,1] neg_hi:[0,1]
	v_pk_add_f32 v[68:69], v[68:69], v[0:1] op_sel_hi:[1,0] neg_lo:[0,1] neg_hi:[0,1]
	v_pk_add_f32 v[84:85], v[84:85], v[0:1] op_sel_hi:[1,0] neg_lo:[0,1] neg_hi:[0,1]
	v_pk_add_f32 v[70:71], v[70:71], v[0:1] op_sel_hi:[1,0] neg_lo:[0,1] neg_hi:[0,1]
	v_pk_add_f32 v[86:87], v[86:87], v[0:1] op_sel_hi:[1,0] neg_lo:[0,1] neg_hi:[0,1]
	v_pk_add_f32 v[72:73], v[72:73], v[0:1] op_sel_hi:[1,0] neg_lo:[0,1] neg_hi:[0,1]
	v_pk_add_f32 v[88:89], v[88:89], v[0:1] op_sel_hi:[1,0] neg_lo:[0,1] neg_hi:[0,1]
	v_pk_add_f32 v[74:75], v[74:75], v[0:1] op_sel_hi:[1,0] neg_lo:[0,1] neg_hi:[0,1]
	v_pk_add_f32 v[90:91], v[90:91], v[0:1] op_sel_hi:[1,0] neg_lo:[0,1] neg_hi:[0,1]
	v_pk_add_f32 v[76:77], v[76:77], v[0:1] op_sel_hi:[1,0] neg_lo:[0,1] neg_hi:[0,1]
	v_pk_add_f32 v[92:93], v[92:93], v[0:1] op_sel_hi:[1,0] neg_lo:[0,1] neg_hi:[0,1]
	v_pk_add_f32 v[78:79], v[78:79], v[0:1] op_sel_hi:[1,0] neg_lo:[0,1] neg_hi:[0,1]
	v_pk_add_f32 v[94:95], v[94:95], v[0:1] op_sel_hi:[1,0] neg_lo:[0,1] neg_hi:[0,1]
	v_pk_mul_f32 v[32:33], v[32:33], v[34:35] op_sel_hi:[1,0]
	v_pk_mul_f32 v[30:31], v[30:31], v[34:35] op_sel_hi:[1,0]
	v_pk_mul_f32 v[28:29], v[28:29], v[34:35] op_sel_hi:[1,0]
	v_pk_mul_f32 v[26:27], v[26:27], v[34:35] op_sel_hi:[1,0]
	v_pk_mul_f32 v[24:25], v[24:25], v[34:35] op_sel_hi:[1,0]
	v_pk_mul_f32 v[22:23], v[22:23], v[34:35] op_sel_hi:[1,0]
	v_pk_mul_f32 v[20:21], v[20:21], v[34:35] op_sel_hi:[1,0]
	v_pk_mul_f32 v[18:19], v[18:19], v[34:35] op_sel_hi:[1,0]
	v_pk_mul_f32 v[16:17], v[16:17], v[34:35] op_sel_hi:[1,0]
	v_pk_mul_f32 v[14:15], v[14:15], v[34:35] op_sel_hi:[1,0]
	v_pk_mul_f32 v[12:13], v[12:13], v[34:35] op_sel_hi:[1,0]
	v_pk_mul_f32 v[10:11], v[10:11], v[34:35] op_sel_hi:[1,0]
	v_pk_mul_f32 v[8:9], v[8:9], v[34:35] op_sel_hi:[1,0]
	v_pk_mul_f32 v[6:7], v[6:7], v[34:35] op_sel_hi:[1,0]
	v_pk_mul_f32 v[4:5], v[4:5], v[34:35] op_sel_hi:[1,0]
	v_pk_mul_f32 v[2:3], v[2:3], v[34:35] op_sel_hi:[1,0]
	v_pk_add_f32 v[80:81], v[80:81], v[0:1] op_sel_hi:[1,0] neg_lo:[0,1] neg_hi:[0,1]
	v_pk_add_f32 v[96:97], v[96:97], v[0:1] op_sel_hi:[1,0] neg_lo:[0,1] neg_hi:[0,1]
	v_mov_b32_e32 v51, v50
	v_mov_b32_e32 v52, v50
	v_mov_b32_e32 v53, v50
	v_mov_b32_e32 v54, v50
	v_mov_b32_e32 v55, v50
	v_mov_b32_e32 v56, v50
	v_mov_b32_e32 v57, v50
	v_mov_b32_e32 v58, v50
	v_mov_b32_e32 v59, v50
	v_mov_b32_e32 v60, v50
	v_mov_b32_e32 v61, v50
	v_mov_b32_e32 v62, v50
	v_mov_b32_e32 v63, v50
	v_mov_b32_e32 v64, v50
	v_mov_b32_e32 v65, v50
	v_mov_b32_e32 v34, v50
	v_mov_b32_e32 v35, v50
	v_mov_b32_e32 v36, v50
	v_mov_b32_e32 v37, v50
	v_mov_b32_e32 v38, v50
	v_mov_b32_e32 v39, v50
	v_mov_b32_e32 v40, v50
	v_mov_b32_e32 v41, v50
	v_mov_b32_e32 v42, v50
	v_mov_b32_e32 v43, v50
	v_mov_b32_e32 v44, v50
	v_mov_b32_e32 v45, v50
	v_mov_b32_e32 v46, v50
	v_mov_b32_e32 v47, v50
	v_mov_b32_e32 v48, v50
	v_mov_b32_e32 v49, v50
	s_branch .LBB0_119
.LBB0_118:
.LBB0_119:
	v_exp_f32_e32 v217, v66
	v_exp_f32_e32 v225, v67
	v_exp_f32_e32 v215, v68
	v_exp_f32_e32 v230, v69
	v_exp_f32_e32 v213, v70
	v_exp_f32_e32 v216, v71
	v_exp_f32_e32 v231, v72
	v_exp_f32_e32 v220, v73
	v_cvt_pk_bf16_f32 v66, v217, v225
	v_cvt_pk_bf16_f32 v67, v215, v230
	v_cvt_pk_bf16_f32 v68, v213, v216
	v_cvt_pk_bf16_f32 v69, v231, v220
	v_exp_f32_e32 v224, v82
	v_exp_f32_e32 v229, v83
	s_waitcnt lgkmcnt(12)
	v_mfma_f32_32x32x16_bf16 v[18:33], v[174:177], v[66:69], v[18:33]
	v_exp_f32_e32 v214, v86
	v_exp_f32_e32 v233, v88
	v_exp_f32_e32 v226, v89
	v_exp_f32_e32 v221, v74
	v_exp_f32_e32 v222, v75
	v_exp_f32_e32 v223, v76
	v_exp_f32_e32 v88, v77
	v_mfma_f32_32x32x16_bf16 v[2:17], v[170:173], v[66:69], v[2:17]
	v_exp_f32_e32 v89, v78
	v_exp_f32_e32 v86, v79
	v_exp_f32_e32 v82, v80
	v_exp_f32_e32 v83, v81
	v_cvt_pk_bf16_f32 v66, v221, v222
	v_cvt_pk_bf16_f32 v67, v223, v88
	v_cvt_pk_bf16_f32 v68, v89, v86
	v_cvt_pk_bf16_f32 v69, v82, v83
	v_exp_f32_e32 v218, v84
	v_exp_f32_e32 v232, v85
	s_waitcnt lgkmcnt(10)
	v_mfma_f32_32x32x16_bf16 v[18:33], v[166:169], v[66:69], v[18:33]
	v_exp_f32_e32 v219, v87
	v_exp_f32_e32 v227, v90
	v_exp_f32_e32 v228, v91
	v_exp_f32_e32 v92, v92
	v_exp_f32_e32 v90, v93
	v_exp_f32_e32 v91, v94
	v_exp_f32_e32 v87, v95
	s_waitcnt lgkmcnt(8)
	v_mfma_f32_32x32x16_bf16 v[2:17], v[162:165], v[66:69], v[2:17]
	v_cvt_pk_bf16_f32 v66, v224, v229
	v_cvt_pk_bf16_f32 v67, v218, v232
	v_cvt_pk_bf16_f32 v68, v214, v219
	v_cvt_pk_bf16_f32 v69, v233, v226
	v_exp_f32_e32 v84, v96
	v_exp_f32_e32 v85, v97
	s_waitcnt lgkmcnt(6)
	v_mfma_f32_32x32x16_bf16 v[18:33], v[158:161], v[66:69], v[18:33]
	s_waitcnt lgkmcnt(4)
	v_mfma_f32_32x32x16_bf16 v[2:17], v[154:157], v[66:69], v[2:17]
	v_cvt_pk_bf16_f32 v66, v227, v228
	v_cvt_pk_bf16_f32 v67, v92, v90
	v_cvt_pk_bf16_f32 v68, v91, v87
	v_cvt_pk_bf16_f32 v69, v84, v85
	s_waitcnt lgkmcnt(2)
	s_nop 0
	v_mfma_f32_32x32x16_bf16 v[18:33], v[146:149], v[66:69], v[18:33]
	s_waitcnt lgkmcnt(0)
	v_mfma_f32_32x32x16_bf16 v[2:17], v[150:153], v[66:69], v[2:17]
	s_and_saveexec_b64 s[0:1], s[6:7]
	s_cbranch_execz .LBB0_121
	s_waitcnt vmcnt(5)
	ds_write_b128 v187, v[122:125] offset:13312

; template <int MODE>
; DI void attn_tile(const Params& p, int layer, int tile, char* smem) {
;     ...
;   lsum = hsum(lsum);
;   const float inv = 1.f / lsum;
;   float sq = 0.f;
; #pragma unroll
;   for (int i = 0; i < 16; ++i) { o0[i] *= inv; o1[i] *= inv; sq += o0[i] * o0[i] + o1[i] * o1[i]; }
;   sq = hsum(sq);
;   if (h == 0) ((float*)(p.ws + OFF_SSQ))[(tok0 + qpos) * 16 + MODE * 4 + head] = sq;
.LBB0_129:
	v_add_f32_e32 v50, v50, v66
	v_add_f32_e32 v50, 0, v50
	v_add_f32_e32 v51, v51, v67
	v_add_f32_e32 v50, v51, v50
	v_add_f32_e32 v51, v52, v68
	v_add_f32_e32 v50, v51, v50
	v_add_f32_e32 v51, v53, v69
	v_add_f32_e32 v50, v51, v50
	v_add_f32_e32 v51, v54, v70
	v_add_f32_e32 v50, v51, v50
	v_add_f32_e32 v51, v55, v71
	v_add_f32_e32 v50, v51, v50
	v_add_f32_e32 v51, v56, v72
	v_add_f32_e32 v50, v51, v50
	v_add_f32_e32 v51, v162, v73
	v_add_f32_e32 v50, v51, v50
	v_add_f32_e32 v51, v74, v57
	v_add_f32_e32 v50, v51, v50
	v_add_f32_e32 v51, v75, v58
	v_add_f32_e32 v50, v51, v50
	v_add_f32_e32 v51, v76, v59
	v_add_f32_e32 v50, v51, v50
	v_add_f32_e32 v51, v77, v60
	v_add_f32_e32 v50, v51, v50
	v_add_f32_e32 v51, v78, v61
	v_add_f32_e32 v50, v51, v50
	v_add_f32_e32 v51, v79, v62
	v_add_f32_e32 v50, v51, v50
	v_add_f32_e32 v51, v80, v63
	v_add_f32_e32 v50, v51, v50
	v_add_f32_e32 v51, v65, v64
	v_add_f32_e32 v50, v51, v50
	v_add_f32_e32 v212, v212, v50
	v_mov_b32_e32 v0, v212
	s_nop 1
	v_permlane32_swap_b32_e32 v212, v0
	v_add_f32_e32 v0, v212, v0
	v_div_scale_f32 v34, s[0:1], v0, v0, 1.0
	v_rcp_f32_e32 v35, v34
	s_nop 0
	v_fma_f32 v36, -v34, v35, 1.0
	v_fmac_f32_e32 v35, v36, v35
	v_div_scale_f32 v36, vcc, 1.0, v0, 1.0
	v_mul_f32_e32 v37, v36, v35
	v_fma_f32 v38, -v34, v37, v36
	v_fmac_f32_e32 v37, v38, v35
	v_fma_f32 v34, -v34, v37, v36
	v_div_fmas_f32 v34, v34, v35, v37
	v_div_fixup_f32 v0, v34, v0, 1.0
	v_pk_mul_f32 v[2:3], v[2:3], v[0:1] op_sel_hi:[1,0]
	v_pk_mul_f32 v[18:19], v[18:19], v[0:1] op_sel_hi:[1,0]
	v_pk_mul_f32 v[34:35], v[2:3], v[2:3]
	v_pk_mul_f32 v[4:5], v[4:5], v[0:1] op_sel_hi:[1,0]
	v_pk_fma_f32 v[34:35], v[18:19], v[18:19], v[34:35]
	v_pk_mul_f32 v[20:21], v[20:21], v[0:1] op_sel_hi:[1,0]
	v_pk_mul_f32 v[36:37], v[4:5], v[4:5]
	v_pk_add_f32 v[34:35], v[34:35], v[34:35] op_sel:[0,1] op_sel_hi:[1,0]
	v_pk_fma_f32 v[36:37], v[20:21], v[20:21], v[36:37]
	v_pk_mul_f32 v[6:7], v[6:7], v[0:1] op_sel_hi:[1,0]
	v_pk_add_f32 v[34:35], v[36:37], v[34:35]
	v_pk_mul_f32 v[22:23], v[22:23], v[0:1] op_sel_hi:[1,0]
	v_pk_add_f32 v[34:35], v[36:37], v[34:35] op_sel:[1,0] op_sel_hi:[0,1]
	v_pk_mul_f32 v[36:37], v[6:7], v[6:7]
	v_pk_mul_f32 v[8:9], v[8:9], v[0:1] op_sel_hi:[1,0]
	v_pk_fma_f32 v[36:37], v[22:23], v[22:23], v[36:37]
	v_pk_mul_f32 v[24:25], v[24:25], v[0:1] op_sel_hi:[1,0]
	v_pk_add_f32 v[34:35], v[36:37], v[34:35]
	v_pk_mul_f32 v[10:11], v[10:11], v[0:1] op_sel_hi:[1,0]
	v_pk_add_f32 v[34:35], v[36:37], v[34:35] op_sel:[1,0] op_sel_hi:[0,1]
	v_pk_mul_f32 v[36:37], v[8:9], v[8:9]
	v_pk_mul_f32 v[26:27], v[26:27], v[0:1] op_sel_hi:[1,0]
	v_pk_fma_f32 v[36:37], v[24:25], v[24:25], v[36:37]
	v_pk_mul_f32 v[12:13], v[12:13], v[0:1] op_sel_hi:[1,0]
	v_pk_add_f32 v[34:35], v[36:37], v[34:35]
	v_pk_mul_f32 v[28:29], v[28:29], v[0:1] op_sel_hi:[1,0]
	v_pk_add_f32 v[34:35], v[36:37], v[34:35] op_sel:[1,0] op_sel_hi:[0,1]
	v_pk_mul_f32 v[36:37], v[10:11], v[10:11]
	v_pk_mul_f32 v[14:15], v[14:15], v[0:1] op_sel_hi:[1,0]
	v_pk_fma_f32 v[36:37], v[26:27], v[26:27], v[36:37]
	v_pk_mul_f32 v[30:31], v[30:31], v[0:1] op_sel_hi:[1,0]
	v_pk_add_f32 v[34:35], v[36:37], v[34:35]
	v_pk_mul_f32 v[16:17], v[16:17], v[0:1] op_sel_hi:[1,0]
	v_pk_add_f32 v[34:35], v[36:37], v[34:35] op_sel:[1,0] op_sel_hi:[0,1]
	v_pk_mul_f32 v[36:37], v[12:13], v[12:13]
	v_pk_mul_f32 v[32:33], v[32:33], v[0:1] op_sel_hi:[1,0]
	v_pk_fma_f32 v[36:37], v[28:29], v[28:29], v[36:37]
	v_cmp_gt_u32_e32 vcc, 32, v183
	v_pk_add_f32 v[34:35], v[36:37], v[34:35]
	s_nop 0
	v_pk_add_f32 v[34:35], v[36:37], v[34:35] op_sel:[1,0] op_sel_hi:[0,1]
	v_pk_mul_f32 v[36:37], v[14:15], v[14:15]
	s_nop 0
	v_pk_fma_f32 v[36:37], v[30:31], v[30:31], v[36:37]
	s_nop 0
	v_pk_add_f32 v[34:35], v[36:37], v[34:35]
	s_nop 0
	v_pk_add_f32 v[34:35], v[36:37], v[34:35] op_sel:[1,0] op_sel_hi:[0,1]
	v_pk_mul_f32 v[36:37], v[16:17], v[16:17]
	s_nop 0
	v_pk_fma_f32 v[36:37], v[32:33], v[32:33], v[36:37]
	s_nop 0
	v_pk_add_f32 v[34:35], v[36:37], v[34:35]
	s_nop 0
	v_pk_add_f32 v[34:35], v[36:37], v[34:35] op_sel:[1,0] op_sel_hi:[0,1]
	v_mov_b32_e32 v0, v34
	s_nop 1
	v_permlane32_swap_b32_e32 v34, v0
	s_and_saveexec_b64 s[0:1], vcc
	s_cbranch_execz .LBB0_101
	v_readlane_b32 s6, v254, 7
	v_lshlrev_b64 v[36:37], 6, v[180:181]
	v_readlane_b32 s7, v254, 8
	s_lshl_b32 s8, s19, 2
	v_add_f32_e32 v0, v34, v0
	v_lshl_add_u64 v[36:37], s[6:7], 0, v[36:37]
	v_readlane_b32 s6, v253, 2
	v_readlane_b32 s7, v253, 3
	s_mov_b32 s9, s7
	v_writelane_b32 v253, s6, 2
	v_lshl_add_u64 v[36:37], v[36:37], 0, s[8:9]
	global_store_dword v[36:37], v0, off
	v_writelane_b32 v253, s7, 3
	s_branch .LBB0_101
